# co-resident workgroup stagger of ~1.3us (half a K-step) at entry of GEMM phases 1,6,7,8
# speedup vs baseline: 1.0049x; 1.0003x over previous
; __global__ void __launch_bounds__(256, 2) hybrid_megakernel(Params p) {
;     ...
;   for (int ph = p.ph_lo; ph < p.ph_hi; ++ph) {
;     const int L = ph / NPH, s = ph % NPH;
;     if (s == 0 && L > 0) continue;
;     ...
;     if (s != ONLY) continue;
;     ...
;     switch (s) {
;       case 0: phase_convert(p, L, smem); break;
;       case 1: phase_in(p, L, smem); break;
;       case 2: phase_prep(p, L, smem); break;
;       case 3: phase_attn1(p, L, smem); break;
;       case 4: phase_attn2(p, smem); break;
;       case 5: phase_widen(p, smem); break;
;       case 6: phase_resid(p, p.u, 1024, p.wt_o, 1024, smem); break;
;       case 7: phase_up(p, smem); break;
;       case 8: phase_resid(p, p.ff, DFF, p.wt_down, DFF, smem); break;
;       case 9: phase_ple(p, L, smem); break;
;     }
.LBB0_4:
	v_writelane_b32 v255, s6, 31
	s_mov_b32 s98, 0x1c2
	s_lshr_b32 s98, s98, s6
	s_bitcmp1_b32 s98, 0
	s_cbranch_scc0 .Lstag_skip
	s_getreg_b32 s98, hwreg(HW_REG_LDS_ALLOC, 0, 12)
	s_cmp_eq_u32 s98, 0
	s_cbranch_scc1 .Lstag_skip
	s_sleep 48
